# P2 GEMM0 epilogue result stores marked non-temporal (read only in later phases)
# baseline (speedup 1.0000x reference)
;     template <int MT> DEVI void operator()(f32x4 (&acc)[MT][4], int row0, int col0, int fr, int fq) const {
;     ...
;                 bf16_t* dst = (t < CTX) ? pqtc + ((size_t)(b * 1024 + e)) * 512 + isq * 256 + t
;                                         : pqt + ((size_t)(b * 1024 + e)) * 8192 + isq * 4096 + (t - CTX);
;                 *(uint2*)dst = o;
.LBB0_233:
	s_or_b64 exec, exec, s[2:3]
	v_cvt_pk_bf16_f32 v3, v2, v3
	v_cvt_pk_bf16_f32 v2, v0, v1
	global_store_dwordx2 v[4:5], v[2:3], off nt

; DEVI unsigned pk2(float lo, float hi) { f32x2 v = {lo, hi}; bf16x2_t b = __builtin_convertvector(v, bf16x2_t); return __builtin_bit_cast(unsigned, b); }
; DEVI float siluf_(float x) { return x * sigmoidf_(x); }
;     template <int MT> DEVI void operator()(f32x4 (&acc)[MT][4], int row0, int col0, int fr, int fq) const {
;         const int type = col0 >> 10;
;         bf16_t* dst = type == 0 ? u : (type == 1 ? sg : sgf);
;         const int cb = (col0 & 1023) + 16 * (fq & 1) + 8 * (fq >> 1);
; #pragma unroll
;         for (int m = 0; m < MT; ++m) {
;             __builtin_amdgcn_sched_barrier(0);
;             bf16_t* rp = dst + (size_t)(row0 + 16 * m + fr) * 1024 + cb;
; #pragma unroll
;             for (int n = 0; n < 4; n += 2) {
;                 f32x4 v = acc[m][n], w_ = acc[m][n + 1];
;                 if (type) { v[0] = siluf_(v[0]); v[1] = siluf_(v[1]); v[2] = siluf_(v[2]); v[3] = siluf_(v[3]);
;                             w_[0] = siluf_(w_[0]); w_[1] = siluf_(w_[1]); w_[2] = siluf_(w_[2]); w_[3] = siluf_(w_[3]); }
;                 uint2 x, y; x.x = pk2(v[0], v[1]); x.y = pk2(v[2], v[3]); y.x = pk2(w_[0], w_[1]); y.y = pk2(w_[2], w_[3]);
;                 *(uint4*)(rp + 16 * n) = widen16(x, y);
;             }
;         }
;     }
.LBB0_248:
	s_or_b64 exec, exec, s[4:5]
	s_movk_i32 s4, 0x800
	v_mov_b32_e32 v133, s54
	v_mov_b32_e32 v134, s82
	v_cmp_gt_u32_e64 s[4:5], s4, v128
	v_mov_b32_e32 v135, s83
	v_lshlrev_b32_e32 v131, 2, v131
	v_cndmask_b32_e64 v133, v133, v134, s[4:5]
	v_mov_b32_e32 v134, s55
	v_cndmask_b32_e64 v134, v134, v135, s[4:5]
	v_mov_b32_e32 v135, s81
	v_lshlrev_b32_e32 v132, 4, v132
	v_and_b32_e32 v131, 8, v131
	v_and_b32_e32 v130, 0xffffff8f, v130
	v_cndmask_b32_e64 v135, v134, v135, s[2:3]
	v_mov_b32_e32 v134, s80
	v_and_b32_e32 v128, 0x3ff, v128
	v_and_or_b32 v131, v132, 16, v131
	v_add_u32_e32 v132, s42, v130
	v_cndmask_b32_e64 v134, v133, v134, s[2:3]
	v_add_lshl_u32 v128, v131, v128, 1
	v_ashrrev_i32_e32 v133, 31, v132
	v_lshl_add_u64 v[130:131], v[134:135], 0, v[128:129]
	v_lshlrev_b64 v[134:135], 11, v[132:133]
	v_cvt_pk_bf16_f32 v124, v124, v125
	v_cvt_pk_bf16_f32 v125, v126, v127
	v_cvt_pk_bf16_f32 v126, v120, v121
	v_cvt_pk_bf16_f32 v127, v122, v123
	v_lshl_add_u64 v[134:135], v[130:131], 0, v[134:135]
	v_permlane16_swap_b32_e32 v124, v126
	v_permlane16_swap_b32_e32 v125, v127
	global_store_dwordx4 v[134:135], v[124:127], off nt
	s_and_saveexec_b64 s[2:3], vcc
	s_cbranch_execz .LBB0_250
	v_mul_f32_e32 v120, 0xbfb8aa3b, v116
	v_mul_f32_e32 v121, 0xbfb8aa3b, v117
	v_mul_f32_e32 v122, 0xbfb8aa3b, v118
	v_mul_f32_e32 v123, 0xbfb8aa3b, v119
	v_exp_f32_e32 v120, v120
	v_exp_f32_e32 v121, v121
	v_exp_f32_e32 v122, v122
	v_exp_f32_e32 v123, v123
	v_add_f32_e32 v120, 1.0, v120
	v_add_f32_e32 v121, 1.0, v121
	v_add_f32_e32 v122, 1.0, v122
	v_add_f32_e32 v123, 1.0, v123
	v_rcp_f32_e32 v120, v120
	v_rcp_f32_e32 v121, v121
	v_rcp_f32_e32 v122, v122
	v_rcp_f32_e32 v123, v123
	v_pk_mul_f32 v[116:117], v[116:117], v[120:121]
	v_mul_f32_e32 v120, 0xbfb8aa3b, v112
	v_pk_mul_f32 v[118:119], v[118:119], v[122:123]
	v_mul_f32_e32 v121, 0xbfb8aa3b, v113
	v_mul_f32_e32 v122, 0xbfb8aa3b, v114
	v_mul_f32_e32 v123, 0xbfb8aa3b, v115
	v_exp_f32_e32 v120, v120
	v_exp_f32_e32 v121, v121
	v_exp_f32_e32 v122, v122
	v_exp_f32_e32 v123, v123
	v_add_f32_e32 v120, 1.0, v120
	v_add_f32_e32 v121, 1.0, v121
	v_add_f32_e32 v122, 1.0, v122
	v_add_f32_e32 v123, 1.0, v123
	v_rcp_f32_e32 v120, v120
	v_rcp_f32_e32 v121, v121
	v_rcp_f32_e32 v122, v122
	v_rcp_f32_e32 v123, v123
	v_pk_mul_f32 v[112:113], v[112:113], v[120:121]
	v_pk_mul_f32 v[114:115], v[114:115], v[122:123]
.LBB0_250:
	s_or_b64 exec, exec, s[2:3]
	v_cvt_pk_bf16_f32 v116, v116, v117
	v_cvt_pk_bf16_f32 v117, v118, v119
	v_cvt_pk_bf16_f32 v118, v112, v113
	v_cvt_pk_bf16_f32 v119, v114, v115
	s_nop 0
	v_permlane16_swap_b32_e32 v116, v118
	v_permlane16_swap_b32_e32 v117, v119
	global_store_dwordx4 v[134:135], v[116:119], off offset:64 nt
	s_and_saveexec_b64 s[2:3], vcc
	s_cbranch_execz .LBB0_252
	v_mul_f32_e32 v112, 0xbfb8aa3b, v108
	v_mul_f32_e32 v113, 0xbfb8aa3b, v109
	v_mul_f32_e32 v114, 0xbfb8aa3b, v110
	v_mul_f32_e32 v115, 0xbfb8aa3b, v111
	v_exp_f32_e32 v112, v112
	v_exp_f32_e32 v113, v113
	v_exp_f32_e32 v114, v114
	v_exp_f32_e32 v115, v115
	v_add_f32_e32 v112, 1.0, v112
	v_add_f32_e32 v113, 1.0, v113
	v_add_f32_e32 v114, 1.0, v114
	v_add_f32_e32 v115, 1.0, v115
	v_rcp_f32_e32 v112, v112
	v_rcp_f32_e32 v113, v113
	v_rcp_f32_e32 v114, v114
	v_rcp_f32_e32 v115, v115
	v_pk_mul_f32 v[108:109], v[108:109], v[112:113]
	v_mul_f32_e32 v112, 0xbfb8aa3b, v104
	v_pk_mul_f32 v[110:111], v[110:111], v[114:115]
	v_mul_f32_e32 v113, 0xbfb8aa3b, v105
	v_mul_f32_e32 v114, 0xbfb8aa3b, v106
	v_mul_f32_e32 v115, 0xbfb8aa3b, v107
	v_exp_f32_e32 v112, v112
	v_exp_f32_e32 v113, v113
	v_exp_f32_e32 v114, v114
	v_exp_f32_e32 v115, v115
	v_add_f32_e32 v112, 1.0, v112
	v_add_f32_e32 v113, 1.0, v113
	v_add_f32_e32 v114, 1.0, v114
	v_add_f32_e32 v115, 1.0, v115
	v_rcp_f32_e32 v112, v112
	v_rcp_f32_e32 v113, v113
	v_rcp_f32_e32 v114, v114
	v_rcp_f32_e32 v115, v115
	v_pk_mul_f32 v[104:105], v[104:105], v[112:113]
	v_pk_mul_f32 v[106:107], v[106:107], v[114:115]
.LBB0_252:
	s_or_b64 exec, exec, s[2:3]
	v_add_u32_e32 v112, 16, v132
	v_ashrrev_i32_e32 v113, 31, v112
	v_lshlrev_b64 v[112:113], 11, v[112:113]
	v_cvt_pk_bf16_f32 v108, v108, v109
	v_cvt_pk_bf16_f32 v109, v110, v111
	v_cvt_pk_bf16_f32 v110, v104, v105
	v_cvt_pk_bf16_f32 v111, v106, v107
	v_lshl_add_u64 v[112:113], v[130:131], 0, v[112:113]
	v_permlane16_swap_b32_e32 v108, v110
	v_permlane16_swap_b32_e32 v109, v111
	global_store_dwordx4 v[112:113], v[108:111], off nt
	s_and_saveexec_b64 s[2:3], vcc
	s_cbranch_execz .LBB0_254
	v_mul_f32_e32 v104, 0xbfb8aa3b, v100
	v_mul_f32_e32 v105, 0xbfb8aa3b, v101
	v_mul_f32_e32 v106, 0xbfb8aa3b, v102
	v_mul_f32_e32 v107, 0xbfb8aa3b, v103
	v_exp_f32_e32 v104, v104
	v_exp_f32_e32 v105, v105
	v_exp_f32_e32 v106, v106
	v_exp_f32_e32 v107, v107
	v_add_f32_e32 v104, 1.0, v104
	v_add_f32_e32 v105, 1.0, v105
	v_add_f32_e32 v106, 1.0, v106
	v_add_f32_e32 v107, 1.0, v107
	v_rcp_f32_e32 v104, v104
	v_rcp_f32_e32 v105, v105
	v_rcp_f32_e32 v106, v106
	v_rcp_f32_e32 v107, v107
	v_pk_mul_f32 v[100:101], v[100:101], v[104:105]
	v_mul_f32_e32 v104, 0xbfb8aa3b, v96
	v_pk_mul_f32 v[102:103], v[102:103], v[106:107]
	v_mul_f32_e32 v105, 0xbfb8aa3b, v97
	v_mul_f32_e32 v106, 0xbfb8aa3b, v98
	v_mul_f32_e32 v107, 0xbfb8aa3b, v99
	v_exp_f32_e32 v104, v104
	v_exp_f32_e32 v105, v105
	v_exp_f32_e32 v106, v106
	v_exp_f32_e32 v107, v107
	v_add_f32_e32 v104, 1.0, v104
	v_add_f32_e32 v105, 1.0, v105
	v_add_f32_e32 v106, 1.0, v106
	v_add_f32_e32 v107, 1.0, v107
	v_rcp_f32_e32 v104, v104
	v_rcp_f32_e32 v105, v105
	v_rcp_f32_e32 v106, v106
	v_rcp_f32_e32 v107, v107
	v_pk_mul_f32 v[96:97], v[96:97], v[104:105]
	v_pk_mul_f32 v[98:99], v[98:99], v[106:107]
; DEVI unsigned pk2(float lo, float hi) { f32x2 v = {lo, hi}; bf16x2_t b = __builtin_convertvector(v, bf16x2_t); return __builtin_bit_cast(unsigned, b); }
; DEVI float siluf_(float x) { return x * sigmoidf_(x); }
;     template <int MT> DEVI void operator()(f32x4 (&acc)[MT][4], int row0, int col0, int fr, int fq) const {
;     ...
; #pragma unroll
;         for (int m = 0; m < MT; ++m) {
;             __builtin_amdgcn_sched_barrier(0);
;             bf16_t* rp = dst + (size_t)(row0 + 16 * m + fr) * 1024 + cb;
; #pragma unroll
;             for (int n = 0; n < 4; n += 2) {
;                 f32x4 v = acc[m][n], w_ = acc[m][n + 1];
;                 if (type) { v[0] = siluf_(v[0]); v[1] = siluf_(v[1]); v[2] = siluf_(v[2]); v[3] = siluf_(v[3]);
;                             w_[0] = siluf_(w_[0]); w_[1] = siluf_(w_[1]); w_[2] = siluf_(w_[2]); w_[3] = siluf_(w_[3]); }
;                 uint2 x, y; x.x = pk2(v[0], v[1]); x.y = pk2(v[2], v[3]); y.x = pk2(w_[0], w_[1]); y.y = pk2(w_[2], w_[3]);
;                 *(uint4*)(rp + 16 * n) = widen16(x, y);
;             }
.LBB0_254:
	s_or_b64 exec, exec, s[2:3]
	v_cvt_pk_bf16_f32 v100, v100, v101
	v_cvt_pk_bf16_f32 v101, v102, v103
	v_cvt_pk_bf16_f32 v102, v96, v97
	v_cvt_pk_bf16_f32 v103, v98, v99
	s_nop 0
	v_permlane16_swap_b32_e32 v100, v102
	v_permlane16_swap_b32_e32 v101, v103
	global_store_dwordx4 v[112:113], v[100:103], off offset:64 nt
	s_and_saveexec_b64 s[2:3], vcc
	s_cbranch_execz .LBB0_256
	v_mul_f32_e32 v96, 0xbfb8aa3b, v92
	v_mul_f32_e32 v97, 0xbfb8aa3b, v93
	v_mul_f32_e32 v98, 0xbfb8aa3b, v94
	v_mul_f32_e32 v99, 0xbfb8aa3b, v95
	v_exp_f32_e32 v96, v96
	v_exp_f32_e32 v97, v97
	v_exp_f32_e32 v98, v98
	v_exp_f32_e32 v99, v99
	v_add_f32_e32 v96, 1.0, v96
	v_add_f32_e32 v97, 1.0, v97
	v_add_f32_e32 v98, 1.0, v98
	v_add_f32_e32 v99, 1.0, v99
	v_rcp_f32_e32 v96, v96
	v_rcp_f32_e32 v97, v97
	v_rcp_f32_e32 v98, v98
	v_rcp_f32_e32 v99, v99
	v_pk_mul_f32 v[92:93], v[92:93], v[96:97]
	v_mul_f32_e32 v96, 0xbfb8aa3b, v88
	v_pk_mul_f32 v[94:95], v[94:95], v[98:99]
	v_mul_f32_e32 v97, 0xbfb8aa3b, v89
	v_mul_f32_e32 v98, 0xbfb8aa3b, v90
	v_mul_f32_e32 v99, 0xbfb8aa3b, v91
	v_exp_f32_e32 v96, v96
	v_exp_f32_e32 v97, v97
	v_exp_f32_e32 v98, v98
	v_exp_f32_e32 v99, v99
	v_add_f32_e32 v96, 1.0, v96
	v_add_f32_e32 v97, 1.0, v97
	v_add_f32_e32 v98, 1.0, v98
	v_add_f32_e32 v99, 1.0, v99
	v_rcp_f32_e32 v96, v96
	v_rcp_f32_e32 v97, v97
	v_rcp_f32_e32 v98, v98
	v_rcp_f32_e32 v99, v99
	v_pk_mul_f32 v[88:89], v[88:89], v[96:97]
	v_pk_mul_f32 v[90:91], v[90:91], v[98:99]
.LBB0_256:
	s_or_b64 exec, exec, s[2:3]
	v_add_u32_e32 v96, 32, v132
	v_ashrrev_i32_e32 v97, 31, v96
	v_lshlrev_b64 v[96:97], 11, v[96:97]
	v_cvt_pk_bf16_f32 v92, v92, v93
	v_cvt_pk_bf16_f32 v93, v94, v95
	v_cvt_pk_bf16_f32 v94, v88, v89
	v_cvt_pk_bf16_f32 v95, v90, v91
	v_lshl_add_u64 v[96:97], v[130:131], 0, v[96:97]
	v_permlane16_swap_b32_e32 v92, v94
	v_permlane16_swap_b32_e32 v93, v95
	global_store_dwordx4 v[96:97], v[92:95], off nt
	s_and_saveexec_b64 s[2:3], vcc
	s_cbranch_execz .LBB0_258
	v_mul_f32_e32 v88, 0xbfb8aa3b, v84
	v_mul_f32_e32 v89, 0xbfb8aa3b, v85
	v_mul_f32_e32 v90, 0xbfb8aa3b, v86
	v_mul_f32_e32 v91, 0xbfb8aa3b, v87
	v_exp_f32_e32 v88, v88
	v_exp_f32_e32 v89, v89
	v_exp_f32_e32 v90, v90
	v_exp_f32_e32 v91, v91
	v_add_f32_e32 v88, 1.0, v88
	v_add_f32_e32 v89, 1.0, v89
	v_add_f32_e32 v90, 1.0, v90
	v_add_f32_e32 v91, 1.0, v91
	v_rcp_f32_e32 v88, v88
	v_rcp_f32_e32 v89, v89
	v_rcp_f32_e32 v90, v90
	v_rcp_f32_e32 v91, v91
	v_pk_mul_f32 v[84:85], v[84:85], v[88:89]
	v_mul_f32_e32 v88, 0xbfb8aa3b, v80
	v_pk_mul_f32 v[86:87], v[86:87], v[90:91]
	v_mul_f32_e32 v89, 0xbfb8aa3b, v81
	v_mul_f32_e32 v90, 0xbfb8aa3b, v82
	v_mul_f32_e32 v91, 0xbfb8aa3b, v83
	v_exp_f32_e32 v88, v88
	v_exp_f32_e32 v89, v89
	v_exp_f32_e32 v90, v90
	v_exp_f32_e32 v91, v91
	v_add_f32_e32 v88, 1.0, v88
	v_add_f32_e32 v89, 1.0, v89
	v_add_f32_e32 v90, 1.0, v90
	v_add_f32_e32 v91, 1.0, v91
	v_rcp_f32_e32 v88, v88
	v_rcp_f32_e32 v89, v89
	v_rcp_f32_e32 v90, v90
	v_rcp_f32_e32 v91, v91
	v_pk_mul_f32 v[80:81], v[80:81], v[88:89]
	v_pk_mul_f32 v[82:83], v[82:83], v[90:91]
.LBB0_258:
	s_or_b64 exec, exec, s[2:3]
	v_cvt_pk_bf16_f32 v84, v84, v85
	v_cvt_pk_bf16_f32 v85, v86, v87
	v_cvt_pk_bf16_f32 v86, v80, v81
	v_cvt_pk_bf16_f32 v87, v82, v83
	s_nop 0
	v_permlane16_swap_b32_e32 v84, v86
	v_permlane16_swap_b32_e32 v85, v87
	global_store_dwordx4 v[96:97], v[84:87], off offset:64 nt
	s_and_saveexec_b64 s[2:3], vcc
	s_cbranch_execz .LBB0_260
	v_mul_f32_e32 v80, 0xbfb8aa3b, v76
	v_mul_f32_e32 v81, 0xbfb8aa3b, v77
	v_mul_f32_e32 v82, 0xbfb8aa3b, v78
	v_mul_f32_e32 v83, 0xbfb8aa3b, v79
	v_exp_f32_e32 v80, v80
	v_exp_f32_e32 v81, v81
	v_exp_f32_e32 v82, v82
	v_exp_f32_e32 v83, v83
	v_add_f32_e32 v80, 1.0, v80
	v_add_f32_e32 v81, 1.0, v81
	v_add_f32_e32 v82, 1.0, v82
	v_add_f32_e32 v83, 1.0, v83
	v_rcp_f32_e32 v80, v80
	v_rcp_f32_e32 v81, v81
	v_rcp_f32_e32 v82, v82
	v_rcp_f32_e32 v83, v83
	v_pk_mul_f32 v[76:77], v[76:77], v[80:81]
	v_mul_f32_e32 v80, 0xbfb8aa3b, v72
	v_pk_mul_f32 v[78:79], v[78:79], v[82:83]
	v_mul_f32_e32 v81, 0xbfb8aa3b, v73
	v_mul_f32_e32 v82, 0xbfb8aa3b, v74
	v_mul_f32_e32 v83, 0xbfb8aa3b, v75
	v_exp_f32_e32 v80, v80
	v_exp_f32_e32 v81, v81
	v_exp_f32_e32 v82, v82
	v_exp_f32_e32 v83, v83
	v_add_f32_e32 v80, 1.0, v80
	v_add_f32_e32 v81, 1.0, v81
	v_add_f32_e32 v82, 1.0, v82
	v_add_f32_e32 v83, 1.0, v83
	v_rcp_f32_e32 v80, v80
	v_rcp_f32_e32 v81, v81
	v_rcp_f32_e32 v82, v82
	v_rcp_f32_e32 v83, v83
	v_pk_mul_f32 v[72:73], v[72:73], v[80:81]
	v_pk_mul_f32 v[74:75], v[74:75], v[82:83]
.LBB0_260:
	s_or_b64 exec, exec, s[2:3]
	v_add_u32_e32 v80, 48, v132
	v_ashrrev_i32_e32 v81, 31, v80
	v_lshlrev_b64 v[80:81], 11, v[80:81]
	v_cvt_pk_bf16_f32 v76, v76, v77
	v_cvt_pk_bf16_f32 v77, v78, v79
	v_cvt_pk_bf16_f32 v78, v72, v73
	v_cvt_pk_bf16_f32 v79, v74, v75
	v_lshl_add_u64 v[80:81], v[130:131], 0, v[80:81]
	v_permlane16_swap_b32_e32 v76, v78
	v_permlane16_swap_b32_e32 v77, v79
	global_store_dwordx4 v[80:81], v[76:79], off nt
	s_and_saveexec_b64 s[2:3], vcc
	s_cbranch_execz .LBB0_262
	v_mul_f32_e32 v72, 0xbfb8aa3b, v68
	v_mul_f32_e32 v73, 0xbfb8aa3b, v69
	v_mul_f32_e32 v74, 0xbfb8aa3b, v70
	v_mul_f32_e32 v75, 0xbfb8aa3b, v71
	v_exp_f32_e32 v72, v72
	v_exp_f32_e32 v73, v73
	v_exp_f32_e32 v74, v74
	v_exp_f32_e32 v75, v75
	v_add_f32_e32 v72, 1.0, v72
	v_add_f32_e32 v73, 1.0, v73
	v_add_f32_e32 v74, 1.0, v74
	v_add_f32_e32 v75, 1.0, v75
	v_rcp_f32_e32 v72, v72
	v_rcp_f32_e32 v73, v73
	v_rcp_f32_e32 v74, v74
	v_rcp_f32_e32 v75, v75
	v_pk_mul_f32 v[68:69], v[68:69], v[72:73]
	v_mul_f32_e32 v72, 0xbfb8aa3b, v64
	v_pk_mul_f32 v[70:71], v[70:71], v[74:75]
	v_mul_f32_e32 v73, 0xbfb8aa3b, v65
	v_mul_f32_e32 v74, 0xbfb8aa3b, v66
	v_mul_f32_e32 v75, 0xbfb8aa3b, v67
	v_exp_f32_e32 v72, v72
	v_exp_f32_e32 v73, v73
	v_exp_f32_e32 v74, v74
	v_exp_f32_e32 v75, v75
	v_add_f32_e32 v72, 1.0, v72
	v_add_f32_e32 v73, 1.0, v73
	v_add_f32_e32 v74, 1.0, v74
	v_add_f32_e32 v75, 1.0, v75
	v_rcp_f32_e32 v72, v72
	v_rcp_f32_e32 v73, v73
	v_rcp_f32_e32 v74, v74
	v_rcp_f32_e32 v75, v75
	v_pk_mul_f32 v[64:65], v[64:65], v[72:73]
	v_pk_mul_f32 v[66:67], v[66:67], v[74:75]
; DEVI unsigned pk2(float lo, float hi) { f32x2 v = {lo, hi}; bf16x2_t b = __builtin_convertvector(v, bf16x2_t); return __builtin_bit_cast(unsigned, b); }
; DEVI float siluf_(float x) { return x * sigmoidf_(x); }
;     template <int MT> DEVI void operator()(f32x4 (&acc)[MT][4], int row0, int col0, int fr, int fq) const {
;     ...
; #pragma unroll
;         for (int m = 0; m < MT; ++m) {
;             __builtin_amdgcn_sched_barrier(0);
;             bf16_t* rp = dst + (size_t)(row0 + 16 * m + fr) * 1024 + cb;
; #pragma unroll
;             for (int n = 0; n < 4; n += 2) {
;                 f32x4 v = acc[m][n], w_ = acc[m][n + 1];
;                 if (type) { v[0] = siluf_(v[0]); v[1] = siluf_(v[1]); v[2] = siluf_(v[2]); v[3] = siluf_(v[3]);
;                             w_[0] = siluf_(w_[0]); w_[1] = siluf_(w_[1]); w_[2] = siluf_(w_[2]); w_[3] = siluf_(w_[3]); }
;                 uint2 x, y; x.x = pk2(v[0], v[1]); x.y = pk2(v[2], v[3]); y.x = pk2(w_[0], w_[1]); y.y = pk2(w_[2], w_[3]);
;                 *(uint4*)(rp + 16 * n) = widen16(x, y);
;             }
.LBB0_262:
	s_or_b64 exec, exec, s[2:3]
	v_cvt_pk_bf16_f32 v68, v68, v69
	v_cvt_pk_bf16_f32 v69, v70, v71
	v_cvt_pk_bf16_f32 v70, v64, v65
	v_cvt_pk_bf16_f32 v71, v66, v67
	s_nop 0
	v_permlane16_swap_b32_e32 v68, v70
	v_permlane16_swap_b32_e32 v69, v71
	global_store_dwordx4 v[80:81], v[68:71], off offset:64 nt
	s_and_saveexec_b64 s[2:3], vcc
	s_cbranch_execz .LBB0_264
	v_mul_f32_e32 v64, 0xbfb8aa3b, v60
	v_mul_f32_e32 v65, 0xbfb8aa3b, v61
	v_mul_f32_e32 v66, 0xbfb8aa3b, v62
	v_mul_f32_e32 v67, 0xbfb8aa3b, v63
	v_exp_f32_e32 v64, v64
	v_exp_f32_e32 v65, v65
	v_exp_f32_e32 v66, v66
	v_exp_f32_e32 v67, v67
	v_add_f32_e32 v64, 1.0, v64
	v_add_f32_e32 v65, 1.0, v65
	v_add_f32_e32 v66, 1.0, v66
	v_add_f32_e32 v67, 1.0, v67
	v_rcp_f32_e32 v64, v64
	v_rcp_f32_e32 v65, v65
	v_rcp_f32_e32 v66, v66
	v_rcp_f32_e32 v67, v67
	v_pk_mul_f32 v[60:61], v[60:61], v[64:65]
	v_mul_f32_e32 v64, 0xbfb8aa3b, v56
	v_pk_mul_f32 v[62:63], v[62:63], v[66:67]
	v_mul_f32_e32 v65, 0xbfb8aa3b, v57
	v_mul_f32_e32 v66, 0xbfb8aa3b, v58
	v_mul_f32_e32 v67, 0xbfb8aa3b, v59
	v_exp_f32_e32 v64, v64
	v_exp_f32_e32 v65, v65
	v_exp_f32_e32 v66, v66
	v_exp_f32_e32 v67, v67
	v_add_f32_e32 v64, 1.0, v64
	v_add_f32_e32 v65, 1.0, v65
	v_add_f32_e32 v66, 1.0, v66
	v_add_f32_e32 v67, 1.0, v67
	v_rcp_f32_e32 v64, v64
	v_rcp_f32_e32 v65, v65
	v_rcp_f32_e32 v66, v66
	v_rcp_f32_e32 v67, v67
	v_pk_mul_f32 v[56:57], v[56:57], v[64:65]
	v_pk_mul_f32 v[58:59], v[58:59], v[66:67]
.LBB0_264:
	s_or_b64 exec, exec, s[2:3]
	v_add_u32_e32 v64, 64, v132
	v_ashrrev_i32_e32 v65, 31, v64
	v_lshlrev_b64 v[64:65], 11, v[64:65]
	v_cvt_pk_bf16_f32 v60, v60, v61
	v_cvt_pk_bf16_f32 v61, v62, v63
	v_cvt_pk_bf16_f32 v62, v56, v57
	v_cvt_pk_bf16_f32 v63, v58, v59
	v_lshl_add_u64 v[64:65], v[130:131], 0, v[64:65]
	v_permlane16_swap_b32_e32 v60, v62
	v_permlane16_swap_b32_e32 v61, v63
	global_store_dwordx4 v[64:65], v[60:63], off nt
	s_and_saveexec_b64 s[2:3], vcc
	s_cbranch_execz .LBB0_266
	v_mul_f32_e32 v56, 0xbfb8aa3b, v52
	v_mul_f32_e32 v57, 0xbfb8aa3b, v53
	v_mul_f32_e32 v58, 0xbfb8aa3b, v54
	v_mul_f32_e32 v59, 0xbfb8aa3b, v55
	v_exp_f32_e32 v56, v56
	v_exp_f32_e32 v57, v57
	v_exp_f32_e32 v58, v58
	v_exp_f32_e32 v59, v59
	v_add_f32_e32 v56, 1.0, v56
	v_add_f32_e32 v57, 1.0, v57
	v_add_f32_e32 v58, 1.0, v58
	v_add_f32_e32 v59, 1.0, v59
	v_rcp_f32_e32 v56, v56
	v_rcp_f32_e32 v57, v57
	v_rcp_f32_e32 v58, v58
	v_rcp_f32_e32 v59, v59
	v_pk_mul_f32 v[52:53], v[52:53], v[56:57]
	v_mul_f32_e32 v56, 0xbfb8aa3b, v48
	v_pk_mul_f32 v[54:55], v[54:55], v[58:59]
	v_mul_f32_e32 v57, 0xbfb8aa3b, v49
	v_mul_f32_e32 v58, 0xbfb8aa3b, v50
	v_mul_f32_e32 v59, 0xbfb8aa3b, v51
	v_exp_f32_e32 v56, v56
	v_exp_f32_e32 v57, v57
	v_exp_f32_e32 v58, v58
	v_exp_f32_e32 v59, v59
	v_add_f32_e32 v56, 1.0, v56
	v_add_f32_e32 v57, 1.0, v57
	v_add_f32_e32 v58, 1.0, v58
	v_add_f32_e32 v59, 1.0, v59
	v_rcp_f32_e32 v56, v56
	v_rcp_f32_e32 v57, v57
	v_rcp_f32_e32 v58, v58
	v_rcp_f32_e32 v59, v59
	v_pk_mul_f32 v[48:49], v[48:49], v[56:57]
	v_pk_mul_f32 v[50:51], v[50:51], v[58:59]
.LBB0_266:
	s_or_b64 exec, exec, s[2:3]
	v_cvt_pk_bf16_f32 v52, v52, v53
	v_cvt_pk_bf16_f32 v53, v54, v55
	v_cvt_pk_bf16_f32 v54, v48, v49
	v_cvt_pk_bf16_f32 v55, v50, v51
	s_nop 0
	v_permlane16_swap_b32_e32 v52, v54
	v_permlane16_swap_b32_e32 v53, v55
	global_store_dwordx4 v[64:65], v[52:55], off offset:64 nt
	s_and_saveexec_b64 s[2:3], vcc
	s_cbranch_execz .LBB0_268
	v_mul_f32_e32 v48, 0xbfb8aa3b, v44
	v_mul_f32_e32 v49, 0xbfb8aa3b, v45
	v_mul_f32_e32 v50, 0xbfb8aa3b, v46
	v_mul_f32_e32 v51, 0xbfb8aa3b, v47
	v_exp_f32_e32 v48, v48
	v_exp_f32_e32 v49, v49
	v_exp_f32_e32 v50, v50
	v_exp_f32_e32 v51, v51
	v_add_f32_e32 v48, 1.0, v48
	v_add_f32_e32 v49, 1.0, v49
	v_add_f32_e32 v50, 1.0, v50
	v_add_f32_e32 v51, 1.0, v51
	v_rcp_f32_e32 v48, v48
	v_rcp_f32_e32 v49, v49
	v_rcp_f32_e32 v50, v50
	v_rcp_f32_e32 v51, v51
	v_pk_mul_f32 v[44:45], v[44:45], v[48:49]
	v_mul_f32_e32 v48, 0xbfb8aa3b, v40
	v_pk_mul_f32 v[46:47], v[46:47], v[50:51]
	v_mul_f32_e32 v49, 0xbfb8aa3b, v41
	v_mul_f32_e32 v50, 0xbfb8aa3b, v42
	v_mul_f32_e32 v51, 0xbfb8aa3b, v43
	v_exp_f32_e32 v48, v48
	v_exp_f32_e32 v49, v49
	v_exp_f32_e32 v50, v50
	v_exp_f32_e32 v51, v51
	v_add_f32_e32 v48, 1.0, v48
	v_add_f32_e32 v49, 1.0, v49
	v_add_f32_e32 v50, 1.0, v50
	v_add_f32_e32 v51, 1.0, v51
	v_rcp_f32_e32 v48, v48
	v_rcp_f32_e32 v49, v49
	v_rcp_f32_e32 v50, v50
	v_rcp_f32_e32 v51, v51
	v_pk_mul_f32 v[40:41], v[40:41], v[48:49]
	v_pk_mul_f32 v[42:43], v[42:43], v[50:51]
.LBB0_268:
	s_or_b64 exec, exec, s[2:3]
	v_add_u32_e32 v48, 0x50, v132
	v_ashrrev_i32_e32 v49, 31, v48
	v_lshlrev_b64 v[48:49], 11, v[48:49]
	v_cvt_pk_bf16_f32 v44, v44, v45
	v_cvt_pk_bf16_f32 v45, v46, v47
	v_cvt_pk_bf16_f32 v46, v40, v41
	v_cvt_pk_bf16_f32 v47, v42, v43
	v_lshl_add_u64 v[48:49], v[130:131], 0, v[48:49]
	v_permlane16_swap_b32_e32 v44, v46
	v_permlane16_swap_b32_e32 v45, v47
	global_store_dwordx4 v[48:49], v[44:47], off nt
	s_and_saveexec_b64 s[2:3], vcc
	s_cbranch_execz .LBB0_270
	v_mul_f32_e32 v40, 0xbfb8aa3b, v36
	v_mul_f32_e32 v41, 0xbfb8aa3b, v37
	v_mul_f32_e32 v42, 0xbfb8aa3b, v38
	v_mul_f32_e32 v43, 0xbfb8aa3b, v39
	v_exp_f32_e32 v40, v40
	v_exp_f32_e32 v41, v41
	v_exp_f32_e32 v42, v42
	v_exp_f32_e32 v43, v43
	v_add_f32_e32 v40, 1.0, v40
	v_add_f32_e32 v41, 1.0, v41
	v_add_f32_e32 v42, 1.0, v42
	v_add_f32_e32 v43, 1.0, v43
	v_rcp_f32_e32 v40, v40
	v_rcp_f32_e32 v41, v41
	v_rcp_f32_e32 v42, v42
	v_rcp_f32_e32 v43, v43
	v_pk_mul_f32 v[36:37], v[36:37], v[40:41]
	v_mul_f32_e32 v40, 0xbfb8aa3b, v32
	v_pk_mul_f32 v[38:39], v[38:39], v[42:43]
	v_mul_f32_e32 v41, 0xbfb8aa3b, v33
	v_mul_f32_e32 v42, 0xbfb8aa3b, v34
	v_mul_f32_e32 v43, 0xbfb8aa3b, v35
	v_exp_f32_e32 v40, v40
	v_exp_f32_e32 v41, v41
	v_exp_f32_e32 v42, v42
	v_exp_f32_e32 v43, v43
	v_add_f32_e32 v40, 1.0, v40
	v_add_f32_e32 v41, 1.0, v41
	v_add_f32_e32 v42, 1.0, v42
	v_add_f32_e32 v43, 1.0, v43
	v_rcp_f32_e32 v40, v40
	v_rcp_f32_e32 v41, v41
	v_rcp_f32_e32 v42, v42
	v_rcp_f32_e32 v43, v43
	v_pk_mul_f32 v[32:33], v[32:33], v[40:41]
	v_pk_mul_f32 v[34:35], v[34:35], v[42:43]
; DEVI unsigned pk2(float lo, float hi) { f32x2 v = {lo, hi}; bf16x2_t b = __builtin_convertvector(v, bf16x2_t); return __builtin_bit_cast(unsigned, b); }
; DEVI float siluf_(float x) { return x * sigmoidf_(x); }
;     template <int MT> DEVI void operator()(f32x4 (&acc)[MT][4], int row0, int col0, int fr, int fq) const {
;     ...
; #pragma unroll
;         for (int m = 0; m < MT; ++m) {
;             __builtin_amdgcn_sched_barrier(0);
;             bf16_t* rp = dst + (size_t)(row0 + 16 * m + fr) * 1024 + cb;
; #pragma unroll
;             for (int n = 0; n < 4; n += 2) {
;                 f32x4 v = acc[m][n], w_ = acc[m][n + 1];
;                 if (type) { v[0] = siluf_(v[0]); v[1] = siluf_(v[1]); v[2] = siluf_(v[2]); v[3] = siluf_(v[3]);
;                             w_[0] = siluf_(w_[0]); w_[1] = siluf_(w_[1]); w_[2] = siluf_(w_[2]); w_[3] = siluf_(w_[3]); }
;                 uint2 x, y; x.x = pk2(v[0], v[1]); x.y = pk2(v[2], v[3]); y.x = pk2(w_[0], w_[1]); y.y = pk2(w_[2], w_[3]);
;                 *(uint4*)(rp + 16 * n) = widen16(x, y);
;             }
.LBB0_270:
	s_or_b64 exec, exec, s[2:3]
	v_cvt_pk_bf16_f32 v36, v36, v37
	v_cvt_pk_bf16_f32 v37, v38, v39
	v_cvt_pk_bf16_f32 v38, v32, v33
	v_cvt_pk_bf16_f32 v39, v34, v35
	s_nop 0
	v_permlane16_swap_b32_e32 v36, v38
	v_permlane16_swap_b32_e32 v37, v39
	global_store_dwordx4 v[48:49], v[36:39], off offset:64 nt
	s_and_saveexec_b64 s[2:3], vcc
	s_cbranch_execz .LBB0_272
	v_mul_f32_e32 v32, 0xbfb8aa3b, v28
	v_mul_f32_e32 v33, 0xbfb8aa3b, v29
	v_mul_f32_e32 v34, 0xbfb8aa3b, v30
	v_mul_f32_e32 v35, 0xbfb8aa3b, v31
	v_exp_f32_e32 v32, v32
	v_exp_f32_e32 v33, v33
	v_exp_f32_e32 v34, v34
	v_exp_f32_e32 v35, v35
	v_add_f32_e32 v32, 1.0, v32
	v_add_f32_e32 v33, 1.0, v33
	v_add_f32_e32 v34, 1.0, v34
	v_add_f32_e32 v35, 1.0, v35
	v_rcp_f32_e32 v32, v32
	v_rcp_f32_e32 v33, v33
	v_rcp_f32_e32 v34, v34
	v_rcp_f32_e32 v35, v35
	v_pk_mul_f32 v[28:29], v[28:29], v[32:33]
	v_mul_f32_e32 v32, 0xbfb8aa3b, v24
	v_pk_mul_f32 v[30:31], v[30:31], v[34:35]
	v_mul_f32_e32 v33, 0xbfb8aa3b, v25
	v_mul_f32_e32 v34, 0xbfb8aa3b, v26
	v_mul_f32_e32 v35, 0xbfb8aa3b, v27
	v_exp_f32_e32 v32, v32
	v_exp_f32_e32 v33, v33
	v_exp_f32_e32 v34, v34
	v_exp_f32_e32 v35, v35
	v_add_f32_e32 v32, 1.0, v32
	v_add_f32_e32 v33, 1.0, v33
	v_add_f32_e32 v34, 1.0, v34
	v_add_f32_e32 v35, 1.0, v35
	v_rcp_f32_e32 v32, v32
	v_rcp_f32_e32 v33, v33
	v_rcp_f32_e32 v34, v34
	v_rcp_f32_e32 v35, v35
	v_pk_mul_f32 v[24:25], v[24:25], v[32:33]
	v_pk_mul_f32 v[26:27], v[26:27], v[34:35]
.LBB0_272:
	s_or_b64 exec, exec, s[2:3]
	v_add_u32_e32 v32, 0x60, v132
	v_ashrrev_i32_e32 v33, 31, v32
	v_lshlrev_b64 v[32:33], 11, v[32:33]
	v_cvt_pk_bf16_f32 v28, v28, v29
	v_cvt_pk_bf16_f32 v29, v30, v31
	v_cvt_pk_bf16_f32 v30, v24, v25
	v_cvt_pk_bf16_f32 v31, v26, v27
	v_lshl_add_u64 v[32:33], v[130:131], 0, v[32:33]
	v_permlane16_swap_b32_e32 v28, v30
	v_permlane16_swap_b32_e32 v29, v31
	global_store_dwordx4 v[32:33], v[28:31], off nt
	s_and_saveexec_b64 s[2:3], vcc
	s_cbranch_execz .LBB0_274
	v_mul_f32_e32 v24, 0xbfb8aa3b, v20
	v_mul_f32_e32 v25, 0xbfb8aa3b, v21
	v_mul_f32_e32 v26, 0xbfb8aa3b, v22
	v_mul_f32_e32 v27, 0xbfb8aa3b, v23
	v_exp_f32_e32 v24, v24
	v_exp_f32_e32 v25, v25
	v_exp_f32_e32 v26, v26
	v_exp_f32_e32 v27, v27
	v_add_f32_e32 v24, 1.0, v24
	v_add_f32_e32 v25, 1.0, v25
	v_add_f32_e32 v26, 1.0, v26
	v_add_f32_e32 v27, 1.0, v27
	v_rcp_f32_e32 v24, v24
	v_rcp_f32_e32 v25, v25
	v_rcp_f32_e32 v26, v26
	v_rcp_f32_e32 v27, v27
	v_pk_mul_f32 v[20:21], v[20:21], v[24:25]
	v_mul_f32_e32 v24, 0xbfb8aa3b, v16
	v_pk_mul_f32 v[22:23], v[22:23], v[26:27]
	v_mul_f32_e32 v25, 0xbfb8aa3b, v17
	v_mul_f32_e32 v26, 0xbfb8aa3b, v18
	v_mul_f32_e32 v27, 0xbfb8aa3b, v19
	v_exp_f32_e32 v24, v24
	v_exp_f32_e32 v25, v25
	v_exp_f32_e32 v26, v26
	v_exp_f32_e32 v27, v27
	v_add_f32_e32 v24, 1.0, v24
	v_add_f32_e32 v25, 1.0, v25
	v_add_f32_e32 v26, 1.0, v26
	v_add_f32_e32 v27, 1.0, v27
	v_rcp_f32_e32 v24, v24
	v_rcp_f32_e32 v25, v25
	v_rcp_f32_e32 v26, v26
	v_rcp_f32_e32 v27, v27
	v_pk_mul_f32 v[16:17], v[16:17], v[24:25]
	v_pk_mul_f32 v[18:19], v[18:19], v[26:27]
.LBB0_274:
	s_or_b64 exec, exec, s[2:3]
	v_cvt_pk_bf16_f32 v20, v20, v21
	v_cvt_pk_bf16_f32 v21, v22, v23
	v_cvt_pk_bf16_f32 v22, v16, v17
	v_cvt_pk_bf16_f32 v23, v18, v19
	s_nop 0
	v_permlane16_swap_b32_e32 v20, v22
	v_permlane16_swap_b32_e32 v21, v23
	global_store_dwordx4 v[32:33], v[20:23], off offset:64 nt
	s_and_saveexec_b64 s[2:3], vcc
	s_cbranch_execz .LBB0_276
	v_mul_f32_e32 v16, 0xbfb8aa3b, v12
	v_mul_f32_e32 v17, 0xbfb8aa3b, v13
	v_mul_f32_e32 v18, 0xbfb8aa3b, v14
	v_mul_f32_e32 v19, 0xbfb8aa3b, v15
	v_exp_f32_e32 v16, v16
	v_exp_f32_e32 v17, v17
	v_exp_f32_e32 v18, v18
	v_exp_f32_e32 v19, v19
	v_add_f32_e32 v16, 1.0, v16
	v_add_f32_e32 v17, 1.0, v17
	v_add_f32_e32 v18, 1.0, v18
	v_add_f32_e32 v19, 1.0, v19
	v_rcp_f32_e32 v16, v16
	v_rcp_f32_e32 v17, v17
	v_rcp_f32_e32 v18, v18
	v_rcp_f32_e32 v19, v19
	v_pk_mul_f32 v[12:13], v[12:13], v[16:17]
	v_mul_f32_e32 v16, 0xbfb8aa3b, v8
	v_pk_mul_f32 v[14:15], v[14:15], v[18:19]
	v_mul_f32_e32 v17, 0xbfb8aa3b, v9
	v_mul_f32_e32 v18, 0xbfb8aa3b, v10
	v_mul_f32_e32 v19, 0xbfb8aa3b, v11
	v_exp_f32_e32 v16, v16
	v_exp_f32_e32 v17, v17
	v_exp_f32_e32 v18, v18
	v_exp_f32_e32 v19, v19
	v_add_f32_e32 v16, 1.0, v16
	v_add_f32_e32 v17, 1.0, v17
	v_add_f32_e32 v18, 1.0, v18
	v_add_f32_e32 v19, 1.0, v19
	v_rcp_f32_e32 v16, v16
	v_rcp_f32_e32 v17, v17
	v_rcp_f32_e32 v18, v18
	v_rcp_f32_e32 v19, v19
	v_pk_mul_f32 v[8:9], v[8:9], v[16:17]
	v_pk_mul_f32 v[10:11], v[10:11], v[18:19]
.LBB0_276:
	s_or_b64 exec, exec, s[2:3]
	v_add_u32_e32 v16, 0x70, v132
	v_ashrrev_i32_e32 v17, 31, v16
	v_lshlrev_b64 v[16:17], 11, v[16:17]
	v_cvt_pk_bf16_f32 v12, v12, v13
	v_cvt_pk_bf16_f32 v13, v14, v15
	v_cvt_pk_bf16_f32 v14, v8, v9
	v_cvt_pk_bf16_f32 v15, v10, v11
	v_lshl_add_u64 v[16:17], v[130:131], 0, v[16:17]
	v_permlane16_swap_b32_e32 v12, v14
	v_permlane16_swap_b32_e32 v13, v15
	global_store_dwordx4 v[16:17], v[12:15], off nt
	s_and_saveexec_b64 s[2:3], vcc
	s_cbranch_execz .LBB0_278
	v_mul_f32_e32 v8, 0xbfb8aa3b, v4
	v_mul_f32_e32 v9, 0xbfb8aa3b, v5
	v_mul_f32_e32 v10, 0xbfb8aa3b, v6
	v_mul_f32_e32 v11, 0xbfb8aa3b, v7
	v_exp_f32_e32 v8, v8
	v_exp_f32_e32 v9, v9
	v_exp_f32_e32 v10, v10
	v_exp_f32_e32 v11, v11
	v_add_f32_e32 v8, 1.0, v8
	v_add_f32_e32 v9, 1.0, v9
	v_add_f32_e32 v10, 1.0, v10
	v_add_f32_e32 v11, 1.0, v11
	v_rcp_f32_e32 v8, v8
	v_rcp_f32_e32 v9, v9
	v_rcp_f32_e32 v10, v10
	v_rcp_f32_e32 v11, v11
	v_pk_mul_f32 v[4:5], v[4:5], v[8:9]
	v_mul_f32_e32 v8, 0xbfb8aa3b, v0
	v_pk_mul_f32 v[6:7], v[6:7], v[10:11]
	v_mul_f32_e32 v9, 0xbfb8aa3b, v1
	v_mul_f32_e32 v10, 0xbfb8aa3b, v2
	v_mul_f32_e32 v11, 0xbfb8aa3b, v3
	v_exp_f32_e32 v8, v8
	v_exp_f32_e32 v9, v9
	v_exp_f32_e32 v10, v10
	v_exp_f32_e32 v11, v11
	v_add_f32_e32 v8, 1.0, v8
	v_add_f32_e32 v9, 1.0, v9
	v_add_f32_e32 v10, 1.0, v10
	v_add_f32_e32 v11, 1.0, v11
	v_rcp_f32_e32 v8, v8
	v_rcp_f32_e32 v9, v9
	v_rcp_f32_e32 v10, v10
	v_rcp_f32_e32 v11, v11
	v_pk_mul_f32 v[0:1], v[0:1], v[8:9]
	v_pk_mul_f32 v[2:3], v[2:3], v[10:11]
.LBB0_278:
	s_or_b64 exec, exec, s[2:3]
	v_cvt_pk_bf16_f32 v4, v4, v5
	v_cvt_pk_bf16_f32 v5, v6, v7
	v_cvt_pk_bf16_f32 v6, v0, v1
	v_cvt_pk_bf16_f32 v7, v2, v3
	s_nop 0
	v_permlane16_swap_b32_e32 v4, v6
	v_permlane16_swap_b32_e32 v5, v7
	global_store_dwordx4 v[16:17], v[4:7], off offset:64 nt
	s_branch .LBB0_234

; DEVI unsigned pk2(float lo, float hi) { f32x2 v = {lo, hi}; bf16x2_t b = __builtin_convertvector(v, bf16x2_t); return __builtin_bit_cast(unsigned, b); }
;     template <int MT> DEVI void operator()(f32x4 (&acc)[MT][4], int row0, int col0, int fr, int fq) const {
;         const int isq = col0 >> 10;
;         const int b = row0 / TPB, t0 = row0 - b * TPB;
; #pragma unroll
;         for (int m = 0; m < MT; ++m)
; #pragma unroll
;             for (int n = 0; n < 4; ++n) {
;                 const int e = (col0 & 1023) + 16 * n + fr;
;                 const int t = t0 + 16 * m + 4 * fq;
;                 f32x4 v = acc[m][n];
;                 uint2 o; o.x = pk2(v[0], v[1]); o.y = pk2(v[2], v[3]);
;                 bf16_t* dst = (t < CTX) ? pqtc + ((size_t)(b * 1024 + e)) * 512 + isq * 256 + t
;                                         : pqt + ((size_t)(b * 1024 + e)) * 8192 + isq * 4096 + (t - CTX);
;                 *(uint2*)dst = o;
;             }
;     }
.LBB0_284:
	v_and_b32_e32 v128, 0xffffff80, v133
	v_add_u32_e32 v128, s42, v128
	s_mov_b32 s2, 0x78787879
	v_mul_hi_i32 v134, v128, s2
	v_lshrrev_b32_e32 v135, 31, v134
	v_ashrrev_i32_e32 v134, 11, v134
	v_lshl_add_u32 v131, v131, 6, s37
	v_add_u32_e32 v134, v134, v135
	v_and_b32_e32 v136, 0x3ff, v131
	v_lshl_or_b32 v132, v134, 10, v132
	v_add_u32_e32 v140, v132, v136
	v_ashrrev_i32_e32 v133, 10, v131
	v_mul_i32_i24_e32 v135, 0xffffef00, v134
	v_lshlrev_b32_e32 v130, 2, v130
	v_ashrrev_i32_e32 v141, 31, v140
	v_add3_u32 v128, v130, v128, v135
	v_lshlrev_b32_e32 v130, 12, v133
	v_lshlrev_b64 v[134:135], 14, v[140:141]
	v_ashrrev_i32_e32 v131, 31, v130
	v_cmp_lt_i32_e32 vcc, s14, v128
	v_lshl_add_u64 v[136:137], s[40:41], 0, v[134:135]
	s_and_saveexec_b64 s[2:3], vcc
	s_xor_b64 s[2:3], exec, s[2:3]
	v_lshl_add_u64 v[134:135], v[130:131], 1, v[136:137]
	v_lshl_add_u64 v[134:135], v[128:129], 1, v[134:135]
	v_lshl_add_u64 v[142:143], v[134:135], 0, s[64:65]
	s_or_saveexec_b64 s[2:3], s[2:3]
	v_readlane_b32 s16, v230, 31
	v_lshlrev_b32_e32 v132, 8, v133
	v_lshlrev_b64 v[138:139], 10, v[140:141]
	v_readlane_b32 s17, v230, 32
	v_ashrrev_i32_e32 v133, 31, v132
	v_ashrrev_i32_e32 v135, 31, v128
	v_mov_b32_e32 v134, v128
	v_lshl_add_u64 v[138:139], s[16:17], 0, v[138:139]
	s_xor_b64 exec, exec, s[2:3]
	v_lshl_add_u64 v[142:143], v[132:133], 1, v[138:139]
	v_lshl_add_u64 v[142:143], v[134:135], 1, v[142:143]
	s_or_b64 exec, exec, s[2:3]
	v_cvt_pk_bf16_f32 v124, v124, v125
	v_cvt_pk_bf16_f32 v125, v126, v127
	v_add_u32_e32 v126, 16, v140
	v_ashrrev_i32_e32 v127, 31, v126
	global_store_dwordx2 v[142:143], v[124:125], off nt
	v_lshlrev_b64 v[124:125], 14, v[126:127]
	v_lshl_add_u64 v[124:125], s[40:41], 0, v[124:125]
	s_and_saveexec_b64 s[2:3], vcc
	s_xor_b64 s[2:3], exec, s[2:3]
	v_lshl_add_u64 v[142:143], v[130:131], 1, v[124:125]
	v_lshl_add_u64 v[142:143], v[128:129], 1, v[142:143]
	v_lshl_add_u64 v[142:143], v[142:143], 0, s[64:65]
	s_or_saveexec_b64 s[2:3], s[2:3]
	v_lshlrev_b64 v[126:127], 10, v[126:127]
	v_lshl_add_u64 v[126:127], s[16:17], 0, v[126:127]
	s_xor_b64 exec, exec, s[2:3]
	v_lshl_add_u64 v[142:143], v[132:133], 1, v[126:127]
	v_lshl_add_u64 v[142:143], v[134:135], 1, v[142:143]
	s_or_b64 exec, exec, s[2:3]
	v_cvt_pk_bf16_f32 v120, v120, v121
	v_cvt_pk_bf16_f32 v121, v122, v123
	v_add_u32_e32 v122, 32, v140
	v_ashrrev_i32_e32 v123, 31, v122
	global_store_dwordx2 v[142:143], v[120:121], off nt
	v_lshlrev_b64 v[120:121], 14, v[122:123]
	v_lshl_add_u64 v[120:121], s[40:41], 0, v[120:121]
	s_and_saveexec_b64 s[2:3], vcc
	s_xor_b64 s[2:3], exec, s[2:3]
	v_lshl_add_u64 v[142:143], v[130:131], 1, v[120:121]
	v_lshl_add_u64 v[142:143], v[128:129], 1, v[142:143]
	v_lshl_add_u64 v[142:143], v[142:143], 0, s[64:65]
	s_or_saveexec_b64 s[2:3], s[2:3]
	v_lshlrev_b64 v[122:123], 10, v[122:123]
	v_lshl_add_u64 v[122:123], s[16:17], 0, v[122:123]
	s_xor_b64 exec, exec, s[2:3]
	v_lshl_add_u64 v[142:143], v[132:133], 1, v[122:123]
	v_lshl_add_u64 v[142:143], v[134:135], 1, v[142:143]
	s_or_b64 exec, exec, s[2:3]
	v_cvt_pk_bf16_f32 v116, v116, v117
	v_cvt_pk_bf16_f32 v117, v118, v119
	v_add_u32_e32 v118, 48, v140
	v_ashrrev_i32_e32 v119, 31, v118
	global_store_dwordx2 v[142:143], v[116:117], off nt
	v_lshlrev_b64 v[116:117], 14, v[118:119]
	v_lshl_add_u64 v[116:117], s[40:41], 0, v[116:117]
	s_and_saveexec_b64 s[2:3], vcc
	s_xor_b64 s[2:3], exec, s[2:3]
	v_lshl_add_u64 v[140:141], v[130:131], 1, v[116:117]
	v_lshl_add_u64 v[140:141], v[128:129], 1, v[140:141]
	v_lshl_add_u64 v[140:141], v[140:141], 0, s[64:65]
	s_or_saveexec_b64 s[2:3], s[2:3]
	v_lshlrev_b64 v[118:119], 10, v[118:119]
	v_lshl_add_u64 v[118:119], s[16:17], 0, v[118:119]
	s_xor_b64 exec, exec, s[2:3]
	v_lshl_add_u64 v[140:141], v[132:133], 1, v[118:119]
	v_lshl_add_u64 v[140:141], v[134:135], 1, v[140:141]
	s_or_b64 exec, exec, s[2:3]
	v_cvt_pk_bf16_f32 v112, v112, v113
	v_cvt_pk_bf16_f32 v113, v114, v115
	global_store_dwordx2 v[140:141], v[112:113], off nt
	v_add_u32_e32 v112, 16, v128
	v_cmp_lt_i32_e32 vcc, s14, v112
	v_mov_b32_e32 v113, v129
	s_and_saveexec_b64 s[2:3], vcc
	s_xor_b64 s[2:3], exec, s[2:3]
	v_lshl_add_u64 v[114:115], v[130:131], 1, v[136:137]
	v_lshl_add_u64 v[114:115], v[112:113], 1, v[114:115]
	v_lshl_add_u64 v[114:115], v[114:115], 0, s[64:65]
	s_andn2_saveexec_b64 s[2:3], s[2:3]
	v_lshl_add_u64 v[114:115], v[132:133], 1, v[138:139]
	v_lshl_add_u64 v[114:115], v[134:135], 1, v[114:115]
	v_lshl_add_u64 v[114:115], v[114:115], 0, 32
	s_or_b64 exec, exec, s[2:3]
	v_cvt_pk_bf16_f32 v108, v108, v109
	v_cvt_pk_bf16_f32 v109, v110, v111
	global_store_dwordx2 v[114:115], v[108:109], off nt
	s_and_saveexec_b64 s[2:3], vcc
	s_xor_b64 s[2:3], exec, s[2:3]
	v_lshl_add_u64 v[108:109], v[130:131], 1, v[124:125]
	v_lshl_add_u64 v[108:109], v[112:113], 1, v[108:109]
	v_lshl_add_u64 v[108:109], v[108:109], 0, s[64:65]
	s_andn2_saveexec_b64 s[2:3], s[2:3]
	v_lshl_add_u64 v[108:109], v[132:133], 1, v[126:127]
	v_lshl_add_u64 v[108:109], v[134:135], 1, v[108:109]
	v_lshl_add_u64 v[108:109], v[108:109], 0, 32
	s_or_b64 exec, exec, s[2:3]
	v_cvt_pk_bf16_f32 v104, v104, v105
	v_cvt_pk_bf16_f32 v105, v106, v107
	global_store_dwordx2 v[108:109], v[104:105], off nt
	s_and_saveexec_b64 s[2:3], vcc
	s_xor_b64 s[2:3], exec, s[2:3]
	v_lshl_add_u64 v[104:105], v[130:131], 1, v[120:121]
	v_lshl_add_u64 v[104:105], v[112:113], 1, v[104:105]
	v_lshl_add_u64 v[104:105], v[104:105], 0, s[64:65]
	s_andn2_saveexec_b64 s[2:3], s[2:3]
	v_lshl_add_u64 v[104:105], v[132:133], 1, v[122:123]
	v_lshl_add_u64 v[104:105], v[134:135], 1, v[104:105]
	v_lshl_add_u64 v[104:105], v[104:105], 0, 32
	s_or_b64 exec, exec, s[2:3]
; DEVI unsigned pk2(float lo, float hi) { f32x2 v = {lo, hi}; bf16x2_t b = __builtin_convertvector(v, bf16x2_t); return __builtin_bit_cast(unsigned, b); }
;     template <int MT> DEVI void operator()(f32x4 (&acc)[MT][4], int row0, int col0, int fr, int fq) const {
;     ...
;         for (int m = 0; m < MT; ++m)
; #pragma unroll
;             for (int n = 0; n < 4; ++n) {
;                 const int e = (col0 & 1023) + 16 * n + fr;
;                 const int t = t0 + 16 * m + 4 * fq;
;                 f32x4 v = acc[m][n];
;                 uint2 o; o.x = pk2(v[0], v[1]); o.y = pk2(v[2], v[3]);
;                 bf16_t* dst = (t < CTX) ? pqtc + ((size_t)(b * 1024 + e)) * 512 + isq * 256 + t
;                                         : pqt + ((size_t)(b * 1024 + e)) * 8192 + isq * 4096 + (t - CTX);
;                 *(uint2*)dst = o;
;             }
	v_cvt_pk_bf16_f32 v100, v100, v101
	v_cvt_pk_bf16_f32 v101, v102, v103
	global_store_dwordx2 v[104:105], v[100:101], off nt
	s_and_saveexec_b64 s[2:3], vcc
	s_xor_b64 s[2:3], exec, s[2:3]
	v_lshl_add_u64 v[100:101], v[130:131], 1, v[116:117]
	v_lshl_add_u64 v[100:101], v[112:113], 1, v[100:101]
	v_lshl_add_u64 v[100:101], v[100:101], 0, s[64:65]
	s_andn2_saveexec_b64 s[2:3], s[2:3]
	v_lshl_add_u64 v[100:101], v[132:133], 1, v[118:119]
	v_lshl_add_u64 v[100:101], v[134:135], 1, v[100:101]
	v_lshl_add_u64 v[100:101], v[100:101], 0, 32
	s_or_b64 exec, exec, s[2:3]
	v_cvt_pk_bf16_f32 v96, v96, v97
	v_cvt_pk_bf16_f32 v97, v98, v99
	global_store_dwordx2 v[100:101], v[96:97], off nt
	v_add_u32_e32 v96, 32, v134
	v_cmp_lt_i32_e32 vcc, s14, v96
	v_mov_b32_e32 v97, v129
	s_and_saveexec_b64 s[2:3], vcc
	s_xor_b64 s[2:3], exec, s[2:3]
	v_lshl_add_u64 v[98:99], v[130:131], 1, v[136:137]
	v_lshl_add_u64 v[98:99], v[96:97], 1, v[98:99]
	v_lshl_add_u64 v[98:99], v[98:99], 0, s[64:65]
	s_andn2_saveexec_b64 s[2:3], s[2:3]
	v_lshl_add_u64 v[98:99], v[132:133], 1, v[138:139]
	v_lshl_add_u64 v[98:99], v[134:135], 1, v[98:99]
	v_lshl_add_u64 v[98:99], v[98:99], 0, 64
	s_or_b64 exec, exec, s[2:3]
	v_cvt_pk_bf16_f32 v92, v92, v93
	v_cvt_pk_bf16_f32 v93, v94, v95
	global_store_dwordx2 v[98:99], v[92:93], off nt
	s_and_saveexec_b64 s[2:3], vcc
	s_xor_b64 s[2:3], exec, s[2:3]
	v_lshl_add_u64 v[92:93], v[130:131], 1, v[124:125]
	v_lshl_add_u64 v[92:93], v[96:97], 1, v[92:93]
	v_lshl_add_u64 v[92:93], v[92:93], 0, s[64:65]
	s_andn2_saveexec_b64 s[2:3], s[2:3]
	v_lshl_add_u64 v[92:93], v[132:133], 1, v[126:127]
	v_lshl_add_u64 v[92:93], v[134:135], 1, v[92:93]
	v_lshl_add_u64 v[92:93], v[92:93], 0, 64
	s_or_b64 exec, exec, s[2:3]
	v_cvt_pk_bf16_f32 v88, v88, v89
	v_cvt_pk_bf16_f32 v89, v90, v91
	global_store_dwordx2 v[92:93], v[88:89], off nt
	s_and_saveexec_b64 s[2:3], vcc
	s_xor_b64 s[2:3], exec, s[2:3]
	v_lshl_add_u64 v[88:89], v[130:131], 1, v[120:121]
	v_lshl_add_u64 v[88:89], v[96:97], 1, v[88:89]
	v_lshl_add_u64 v[88:89], v[88:89], 0, s[64:65]
	s_andn2_saveexec_b64 s[2:3], s[2:3]
	v_lshl_add_u64 v[88:89], v[132:133], 1, v[122:123]
	v_lshl_add_u64 v[88:89], v[134:135], 1, v[88:89]
	v_lshl_add_u64 v[88:89], v[88:89], 0, 64
	s_or_b64 exec, exec, s[2:3]
	v_cvt_pk_bf16_f32 v84, v84, v85
	v_cvt_pk_bf16_f32 v85, v86, v87
	global_store_dwordx2 v[88:89], v[84:85], off nt
	s_and_saveexec_b64 s[2:3], vcc
	s_xor_b64 s[2:3], exec, s[2:3]
	v_lshl_add_u64 v[84:85], v[130:131], 1, v[116:117]
	v_lshl_add_u64 v[84:85], v[96:97], 1, v[84:85]
	v_lshl_add_u64 v[84:85], v[84:85], 0, s[64:65]
	s_andn2_saveexec_b64 s[2:3], s[2:3]
	v_lshl_add_u64 v[84:85], v[132:133], 1, v[118:119]
	v_lshl_add_u64 v[84:85], v[134:135], 1, v[84:85]
	v_lshl_add_u64 v[84:85], v[84:85], 0, 64
	s_or_b64 exec, exec, s[2:3]
	v_cvt_pk_bf16_f32 v80, v80, v81
	v_cvt_pk_bf16_f32 v81, v82, v83
	global_store_dwordx2 v[84:85], v[80:81], off nt
	v_add_u32_e32 v80, 48, v128
	v_cmp_lt_i32_e32 vcc, s14, v80
	v_mov_b32_e32 v81, v129
	s_and_saveexec_b64 s[2:3], vcc
	s_xor_b64 s[2:3], exec, s[2:3]
	v_lshl_add_u64 v[82:83], v[130:131], 1, v[136:137]
	v_lshl_add_u64 v[82:83], v[80:81], 1, v[82:83]
	v_lshl_add_u64 v[82:83], v[82:83], 0, s[64:65]
	s_andn2_saveexec_b64 s[2:3], s[2:3]
	v_lshl_add_u64 v[82:83], v[132:133], 1, v[138:139]
	v_lshl_add_u64 v[82:83], v[134:135], 1, v[82:83]
	v_lshl_add_u64 v[82:83], v[82:83], 0, s[68:69]
	s_or_b64 exec, exec, s[2:3]
	v_cvt_pk_bf16_f32 v76, v76, v77
	v_cvt_pk_bf16_f32 v77, v78, v79
	global_store_dwordx2 v[82:83], v[76:77], off nt
	s_and_saveexec_b64 s[2:3], vcc
	s_xor_b64 s[2:3], exec, s[2:3]
	v_lshl_add_u64 v[76:77], v[130:131], 1, v[124:125]
	v_lshl_add_u64 v[76:77], v[80:81], 1, v[76:77]
	v_lshl_add_u64 v[76:77], v[76:77], 0, s[64:65]
	s_andn2_saveexec_b64 s[2:3], s[2:3]
	v_lshl_add_u64 v[76:77], v[132:133], 1, v[126:127]
	v_lshl_add_u64 v[76:77], v[134:135], 1, v[76:77]
	v_lshl_add_u64 v[76:77], v[76:77], 0, s[68:69]
	s_or_b64 exec, exec, s[2:3]
	v_cvt_pk_bf16_f32 v72, v72, v73
	v_cvt_pk_bf16_f32 v73, v74, v75
	global_store_dwordx2 v[76:77], v[72:73], off nt
	s_and_saveexec_b64 s[2:3], vcc
	s_xor_b64 s[2:3], exec, s[2:3]
	v_lshl_add_u64 v[72:73], v[130:131], 1, v[120:121]
	v_lshl_add_u64 v[72:73], v[80:81], 1, v[72:73]
	v_lshl_add_u64 v[72:73], v[72:73], 0, s[64:65]
	s_andn2_saveexec_b64 s[2:3], s[2:3]
	v_lshl_add_u64 v[72:73], v[132:133], 1, v[122:123]
	v_lshl_add_u64 v[72:73], v[134:135], 1, v[72:73]
	v_lshl_add_u64 v[72:73], v[72:73], 0, s[68:69]
	s_or_b64 exec, exec, s[2:3]
	v_cvt_pk_bf16_f32 v68, v68, v69
	v_cvt_pk_bf16_f32 v69, v70, v71
	global_store_dwordx2 v[72:73], v[68:69], off nt
	s_and_saveexec_b64 s[2:3], vcc
	s_xor_b64 s[2:3], exec, s[2:3]
	v_lshl_add_u64 v[68:69], v[130:131], 1, v[116:117]
	v_lshl_add_u64 v[68:69], v[80:81], 1, v[68:69]
	v_lshl_add_u64 v[68:69], v[68:69], 0, s[64:65]
	s_andn2_saveexec_b64 s[2:3], s[2:3]
	v_lshl_add_u64 v[68:69], v[132:133], 1, v[118:119]
	v_lshl_add_u64 v[68:69], v[134:135], 1, v[68:69]
	v_lshl_add_u64 v[68:69], v[68:69], 0, s[68:69]
	s_or_b64 exec, exec, s[2:3]
	v_cvt_pk_bf16_f32 v64, v64, v65
	v_cvt_pk_bf16_f32 v65, v66, v67
	global_store_dwordx2 v[68:69], v[64:65], off nt
	v_add_u32_e32 v64, 64, v134
	v_cmp_lt_i32_e32 vcc, s14, v64
	v_mov_b32_e32 v65, v129
	s_and_saveexec_b64 s[2:3], vcc
	s_xor_b64 s[2:3], exec, s[2:3]
	v_lshl_add_u64 v[66:67], v[130:131], 1, v[136:137]
	v_lshl_add_u64 v[66:67], v[64:65], 1, v[66:67]
	v_lshl_add_u64 v[66:67], v[66:67], 0, s[64:65]
	s_andn2_saveexec_b64 s[2:3], s[2:3]
	v_lshl_add_u64 v[66:67], v[132:133], 1, v[138:139]
	v_lshl_add_u64 v[66:67], v[134:135], 1, v[66:67]
	v_lshl_add_u64 v[66:67], v[66:67], 0, s[6:7]
; DEVI unsigned pk2(float lo, float hi) { f32x2 v = {lo, hi}; bf16x2_t b = __builtin_convertvector(v, bf16x2_t); return __builtin_bit_cast(unsigned, b); }
;     template <int MT> DEVI void operator()(f32x4 (&acc)[MT][4], int row0, int col0, int fr, int fq) const {
;     ...
;         for (int m = 0; m < MT; ++m)
; #pragma unroll
;             for (int n = 0; n < 4; ++n) {
;                 const int e = (col0 & 1023) + 16 * n + fr;
;                 const int t = t0 + 16 * m + 4 * fq;
;                 f32x4 v = acc[m][n];
;                 uint2 o; o.x = pk2(v[0], v[1]); o.y = pk2(v[2], v[3]);
;                 bf16_t* dst = (t < CTX) ? pqtc + ((size_t)(b * 1024 + e)) * 512 + isq * 256 + t
;                                         : pqt + ((size_t)(b * 1024 + e)) * 8192 + isq * 4096 + (t - CTX);
;                 *(uint2*)dst = o;
;             }
	s_or_b64 exec, exec, s[2:3]
	v_cvt_pk_bf16_f32 v60, v60, v61
	v_cvt_pk_bf16_f32 v61, v62, v63
	global_store_dwordx2 v[66:67], v[60:61], off nt
	s_and_saveexec_b64 s[2:3], vcc
	s_xor_b64 s[2:3], exec, s[2:3]
	v_lshl_add_u64 v[60:61], v[130:131], 1, v[124:125]
	v_lshl_add_u64 v[60:61], v[64:65], 1, v[60:61]
	v_lshl_add_u64 v[60:61], v[60:61], 0, s[64:65]
	s_andn2_saveexec_b64 s[2:3], s[2:3]
	v_lshl_add_u64 v[60:61], v[132:133], 1, v[126:127]
	v_lshl_add_u64 v[60:61], v[134:135], 1, v[60:61]
	v_lshl_add_u64 v[60:61], v[60:61], 0, s[6:7]
	s_or_b64 exec, exec, s[2:3]
	v_cvt_pk_bf16_f32 v56, v56, v57
	v_cvt_pk_bf16_f32 v57, v58, v59
	global_store_dwordx2 v[60:61], v[56:57], off nt
	s_and_saveexec_b64 s[2:3], vcc
	s_xor_b64 s[2:3], exec, s[2:3]
	v_lshl_add_u64 v[56:57], v[130:131], 1, v[120:121]
	v_lshl_add_u64 v[56:57], v[64:65], 1, v[56:57]
	v_lshl_add_u64 v[56:57], v[56:57], 0, s[64:65]
	s_andn2_saveexec_b64 s[2:3], s[2:3]
	v_lshl_add_u64 v[56:57], v[132:133], 1, v[122:123]
	v_lshl_add_u64 v[56:57], v[134:135], 1, v[56:57]
	v_lshl_add_u64 v[56:57], v[56:57], 0, s[6:7]
	s_or_b64 exec, exec, s[2:3]
	v_cvt_pk_bf16_f32 v52, v52, v53
	v_cvt_pk_bf16_f32 v53, v54, v55
	global_store_dwordx2 v[56:57], v[52:53], off nt
	s_and_saveexec_b64 s[2:3], vcc
	s_xor_b64 s[2:3], exec, s[2:3]
	v_lshl_add_u64 v[52:53], v[130:131], 1, v[116:117]
	v_lshl_add_u64 v[52:53], v[64:65], 1, v[52:53]
	v_lshl_add_u64 v[52:53], v[52:53], 0, s[64:65]
	s_andn2_saveexec_b64 s[2:3], s[2:3]
	v_lshl_add_u64 v[52:53], v[132:133], 1, v[118:119]
	v_lshl_add_u64 v[52:53], v[134:135], 1, v[52:53]
	v_lshl_add_u64 v[52:53], v[52:53], 0, s[6:7]
	s_or_b64 exec, exec, s[2:3]
	v_cvt_pk_bf16_f32 v48, v48, v49
	v_cvt_pk_bf16_f32 v49, v50, v51
	global_store_dwordx2 v[52:53], v[48:49], off nt
	v_add_u32_e32 v48, 0x50, v128
	v_cmp_lt_i32_e32 vcc, s14, v48
	v_mov_b32_e32 v49, v129
	s_and_saveexec_b64 s[2:3], vcc
	s_xor_b64 s[2:3], exec, s[2:3]
	v_lshl_add_u64 v[50:51], v[130:131], 1, v[136:137]
	v_lshl_add_u64 v[50:51], v[48:49], 1, v[50:51]
	v_lshl_add_u64 v[50:51], v[50:51], 0, s[64:65]
	s_andn2_saveexec_b64 s[2:3], s[2:3]
	v_lshl_add_u64 v[50:51], v[132:133], 1, v[138:139]
	v_lshl_add_u64 v[50:51], v[134:135], 1, v[50:51]
	v_lshl_add_u64 v[50:51], v[50:51], 0, s[74:75]
	s_or_b64 exec, exec, s[2:3]
	v_cvt_pk_bf16_f32 v44, v44, v45
	v_cvt_pk_bf16_f32 v45, v46, v47
	global_store_dwordx2 v[50:51], v[44:45], off nt
	s_and_saveexec_b64 s[2:3], vcc
	s_xor_b64 s[2:3], exec, s[2:3]
	v_lshl_add_u64 v[44:45], v[130:131], 1, v[124:125]
	v_lshl_add_u64 v[44:45], v[48:49], 1, v[44:45]
	v_lshl_add_u64 v[44:45], v[44:45], 0, s[64:65]
	s_andn2_saveexec_b64 s[2:3], s[2:3]
	v_lshl_add_u64 v[44:45], v[132:133], 1, v[126:127]
	v_lshl_add_u64 v[44:45], v[134:135], 1, v[44:45]
	v_lshl_add_u64 v[44:45], v[44:45], 0, s[74:75]
	s_or_b64 exec, exec, s[2:3]
	v_cvt_pk_bf16_f32 v40, v40, v41
	v_cvt_pk_bf16_f32 v41, v42, v43
	global_store_dwordx2 v[44:45], v[40:41], off nt
	s_and_saveexec_b64 s[2:3], vcc
	s_xor_b64 s[2:3], exec, s[2:3]
	v_lshl_add_u64 v[40:41], v[130:131], 1, v[120:121]
	v_lshl_add_u64 v[40:41], v[48:49], 1, v[40:41]
	v_lshl_add_u64 v[40:41], v[40:41], 0, s[64:65]
	s_andn2_saveexec_b64 s[2:3], s[2:3]
	v_lshl_add_u64 v[40:41], v[132:133], 1, v[122:123]
	v_lshl_add_u64 v[40:41], v[134:135], 1, v[40:41]
	v_lshl_add_u64 v[40:41], v[40:41], 0, s[74:75]
	s_or_b64 exec, exec, s[2:3]
	v_cvt_pk_bf16_f32 v36, v36, v37
	v_cvt_pk_bf16_f32 v37, v38, v39
	global_store_dwordx2 v[40:41], v[36:37], off nt
	s_and_saveexec_b64 s[2:3], vcc
	s_xor_b64 s[2:3], exec, s[2:3]
	v_lshl_add_u64 v[36:37], v[130:131], 1, v[116:117]
	v_lshl_add_u64 v[36:37], v[48:49], 1, v[36:37]
	v_lshl_add_u64 v[36:37], v[36:37], 0, s[64:65]
	s_andn2_saveexec_b64 s[2:3], s[2:3]
	v_lshl_add_u64 v[36:37], v[132:133], 1, v[118:119]
	v_lshl_add_u64 v[36:37], v[134:135], 1, v[36:37]
	v_lshl_add_u64 v[36:37], v[36:37], 0, s[74:75]
	s_or_b64 exec, exec, s[2:3]
	v_cvt_pk_bf16_f32 v32, v32, v33
	v_cvt_pk_bf16_f32 v33, v34, v35
	global_store_dwordx2 v[36:37], v[32:33], off nt
	v_add_u32_e32 v32, 0x60, v134
	v_cmp_lt_i32_e32 vcc, s14, v32
	v_mov_b32_e32 v33, v129
	s_and_saveexec_b64 s[2:3], vcc
	s_xor_b64 s[2:3], exec, s[2:3]
; DEVI unsigned pk2(float lo, float hi) { f32x2 v = {lo, hi}; bf16x2_t b = __builtin_convertvector(v, bf16x2_t); return __builtin_bit_cast(unsigned, b); }
;     template <int MT> DEVI void operator()(f32x4 (&acc)[MT][4], int row0, int col0, int fr, int fq) const {
;     ...
;         for (int m = 0; m < MT; ++m)
; #pragma unroll
;             for (int n = 0; n < 4; ++n) {
;                 const int e = (col0 & 1023) + 16 * n + fr;
;                 const int t = t0 + 16 * m + 4 * fq;
;                 f32x4 v = acc[m][n];
;                 uint2 o; o.x = pk2(v[0], v[1]); o.y = pk2(v[2], v[3]);
;                 bf16_t* dst = (t < CTX) ? pqtc + ((size_t)(b * 1024 + e)) * 512 + isq * 256 + t
;                                         : pqt + ((size_t)(b * 1024 + e)) * 8192 + isq * 4096 + (t - CTX);
;                 *(uint2*)dst = o;
;             }
	v_lshl_add_u64 v[34:35], v[130:131], 1, v[136:137]
	v_lshl_add_u64 v[34:35], v[32:33], 1, v[34:35]
	v_lshl_add_u64 v[34:35], v[34:35], 0, s[64:65]
	s_andn2_saveexec_b64 s[2:3], s[2:3]
	v_lshl_add_u64 v[34:35], v[132:133], 1, v[138:139]
	v_lshl_add_u64 v[34:35], v[134:135], 1, v[34:35]
	v_lshl_add_u64 v[34:35], v[34:35], 0, s[78:79]
	s_or_b64 exec, exec, s[2:3]
	v_cvt_pk_bf16_f32 v28, v28, v29
	v_cvt_pk_bf16_f32 v29, v30, v31
	global_store_dwordx2 v[34:35], v[28:29], off nt
	s_and_saveexec_b64 s[2:3], vcc
	s_xor_b64 s[2:3], exec, s[2:3]
	v_lshl_add_u64 v[28:29], v[130:131], 1, v[124:125]
	v_lshl_add_u64 v[28:29], v[32:33], 1, v[28:29]
	v_lshl_add_u64 v[28:29], v[28:29], 0, s[64:65]
	s_andn2_saveexec_b64 s[2:3], s[2:3]
	v_lshl_add_u64 v[28:29], v[132:133], 1, v[126:127]
	v_lshl_add_u64 v[28:29], v[134:135], 1, v[28:29]
	v_lshl_add_u64 v[28:29], v[28:29], 0, s[78:79]
	s_or_b64 exec, exec, s[2:3]
	v_cvt_pk_bf16_f32 v24, v24, v25
	v_cvt_pk_bf16_f32 v25, v26, v27
	global_store_dwordx2 v[28:29], v[24:25], off nt
	s_and_saveexec_b64 s[2:3], vcc
	s_xor_b64 s[2:3], exec, s[2:3]
	v_lshl_add_u64 v[24:25], v[130:131], 1, v[120:121]
	v_lshl_add_u64 v[24:25], v[32:33], 1, v[24:25]
	v_lshl_add_u64 v[24:25], v[24:25], 0, s[64:65]
	s_andn2_saveexec_b64 s[2:3], s[2:3]
	v_lshl_add_u64 v[24:25], v[132:133], 1, v[122:123]
	v_lshl_add_u64 v[24:25], v[134:135], 1, v[24:25]
	v_lshl_add_u64 v[24:25], v[24:25], 0, s[78:79]
	s_or_b64 exec, exec, s[2:3]
	v_cvt_pk_bf16_f32 v20, v20, v21
	v_cvt_pk_bf16_f32 v21, v22, v23
	global_store_dwordx2 v[24:25], v[20:21], off nt
	s_and_saveexec_b64 s[2:3], vcc
	s_xor_b64 s[2:3], exec, s[2:3]
	v_lshl_add_u64 v[20:21], v[130:131], 1, v[116:117]
	v_lshl_add_u64 v[20:21], v[32:33], 1, v[20:21]
	v_lshl_add_u64 v[20:21], v[20:21], 0, s[64:65]
	s_andn2_saveexec_b64 s[2:3], s[2:3]
	v_lshl_add_u64 v[20:21], v[132:133], 1, v[118:119]
	v_lshl_add_u64 v[20:21], v[134:135], 1, v[20:21]
	v_lshl_add_u64 v[20:21], v[20:21], 0, s[78:79]
	s_or_b64 exec, exec, s[2:3]
	v_add_u32_e32 v128, 0x70, v128
	v_cvt_pk_bf16_f32 v16, v16, v17
	v_cvt_pk_bf16_f32 v17, v18, v19
	v_cmp_lt_i32_e32 vcc, s14, v128
	global_store_dwordx2 v[20:21], v[16:17], off nt
	s_and_saveexec_b64 s[2:3], vcc
	s_xor_b64 s[2:3], exec, s[2:3]
	v_lshl_add_u64 v[16:17], v[130:131], 1, v[136:137]
	v_lshl_add_u64 v[16:17], v[128:129], 1, v[16:17]
	v_lshl_add_u64 v[16:17], v[16:17], 0, s[64:65]
	s_andn2_saveexec_b64 s[2:3], s[2:3]
	v_lshl_add_u64 v[16:17], v[132:133], 1, v[138:139]
	v_lshl_add_u64 v[16:17], v[134:135], 1, v[16:17]
	v_lshl_add_u64 v[16:17], v[16:17], 0, s[86:87]
	s_or_b64 exec, exec, s[2:3]
	v_cvt_pk_bf16_f32 v12, v12, v13
	v_cvt_pk_bf16_f32 v13, v14, v15
	global_store_dwordx2 v[16:17], v[12:13], off nt
	s_and_saveexec_b64 s[2:3], vcc
	s_xor_b64 s[2:3], exec, s[2:3]
	v_lshl_add_u64 v[12:13], v[130:131], 1, v[124:125]
	v_lshl_add_u64 v[12:13], v[128:129], 1, v[12:13]
	v_lshl_add_u64 v[12:13], v[12:13], 0, s[64:65]
	s_andn2_saveexec_b64 s[2:3], s[2:3]
	v_lshl_add_u64 v[12:13], v[132:133], 1, v[126:127]
	v_lshl_add_u64 v[12:13], v[134:135], 1, v[12:13]
	v_lshl_add_u64 v[12:13], v[12:13], 0, s[86:87]
	s_or_b64 exec, exec, s[2:3]
	v_cvt_pk_bf16_f32 v8, v8, v9
	v_cvt_pk_bf16_f32 v9, v10, v11
	global_store_dwordx2 v[12:13], v[8:9], off nt
	s_and_saveexec_b64 s[2:3], vcc
	s_xor_b64 s[2:3], exec, s[2:3]
	v_lshl_add_u64 v[8:9], v[130:131], 1, v[120:121]
	v_lshl_add_u64 v[8:9], v[128:129], 1, v[8:9]
	v_lshl_add_u64 v[8:9], v[8:9], 0, s[64:65]
	s_andn2_saveexec_b64 s[2:3], s[2:3]
	v_lshl_add_u64 v[8:9], v[132:133], 1, v[122:123]
	v_lshl_add_u64 v[8:9], v[134:135], 1, v[8:9]
	v_lshl_add_u64 v[8:9], v[8:9], 0, s[86:87]
	s_or_b64 exec, exec, s[2:3]
	v_cvt_pk_bf16_f32 v4, v4, v5
	v_cvt_pk_bf16_f32 v5, v6, v7
	global_store_dwordx2 v[8:9], v[4:5], off nt
	s_and_saveexec_b64 s[2:3], vcc
	s_xor_b64 s[2:3], exec, s[2:3]
	v_lshl_add_u64 v[4:5], v[130:131], 1, v[116:117]
	v_lshl_add_u64 v[4:5], v[128:129], 1, v[4:5]
	v_lshl_add_u64 v[4:5], v[4:5], 0, s[64:65]
	s_andn2_saveexec_b64 s[2:3], s[2:3]
	s_cbranch_execz .LBB0_233
	v_lshl_add_u64 v[4:5], v[132:133], 1, v[118:119]
	v_lshl_add_u64 v[4:5], v[134:135], 1, v[4:5]
	v_lshl_add_u64 v[4:5], v[4:5], 0, s[86:87]
	s_branch .LBB0_233
